# P7 epilogue: silu gate computed with packed f32 mul/add (same ops and order), 16 instead of 24 VALU per row block
# baseline (speedup 1.0000x reference)
.LBB0_692:
	s_waitcnt vmcnt(0)
	v_fmamk_f32 v198, v198, 0x3a800000, v215
	s_mov_b32 s98, 0xbfb8aa3b
	s_mov_b32 s99, 0xbfb8aa3b
	s_mov_b32 s100, 1.0
	s_mov_b32 s101, 1.0
	v_rsq_f32_e32 v198, v198
	s_cmp_lt_i32 s16, 32
	s_cselect_b32 s0, 2, 0xc2
	s_cmp_lg_u32 s16, 0
	v_pk_fma_f32 v[158:159], v[158:159], v[198:199], v[142:143] op_sel_hi:[1,0,1]
	v_pk_fma_f32 v[156:157], v[156:157], v[198:199], v[140:141] op_sel_hi:[1,0,1]
	v_pk_fma_f32 v[154:155], v[154:155], v[198:199], v[138:139] op_sel_hi:[1,0,1]
	v_pk_fma_f32 v[152:153], v[152:153], v[198:199], v[136:137] op_sel_hi:[1,0,1]
	s_cselect_b32 s46, s0, 0
	s_nop 1
	v_mov_b32_dpp v222, v156 row_ror:1 row_mask:0xf bank_mask:0xf
	v_mov_b32_dpp v226, v156 row_ror:2 row_mask:0xf bank_mask:0xf
	v_mov_b32_dpp v223, v157 row_ror:1 row_mask:0xf bank_mask:0xf
	v_mov_b32_dpp v227, v157 row_ror:2 row_mask:0xf bank_mask:0xf
	v_mov_b32_dpp v224, v158 row_ror:1 row_mask:0xf bank_mask:0xf
	v_mov_b32_dpp v228, v158 row_ror:2 row_mask:0xf bank_mask:0xf
	v_mov_b32_dpp v225, v159 row_ror:1 row_mask:0xf bank_mask:0xf
	v_mov_b32_dpp v229, v159 row_ror:2 row_mask:0xf bank_mask:0xf
	v_mov_b32_dpp v230, v152 row_ror:1 row_mask:0xf bank_mask:0xf
	v_mov_b32_dpp v233, v152 row_ror:2 row_mask:0xf bank_mask:0xf
	v_mov_b32_dpp v231, v153 row_ror:1 row_mask:0xf bank_mask:0xf
	v_mov_b32_dpp v236, v153 row_ror:2 row_mask:0xf bank_mask:0xf
	v_mov_b32_dpp v234, v154 row_ror:1 row_mask:0xf bank_mask:0xf
	v_mov_b32_dpp v239, v154 row_ror:2 row_mask:0xf bank_mask:0xf
	v_mov_b32_dpp v237, v155 row_ror:1 row_mask:0xf bank_mask:0xf
	v_mov_b32_dpp v240, v155 row_ror:2 row_mask:0xf bank_mask:0xf
	v_cmp_le_u32_e64 s[0:1], s46, v200
	s_and_saveexec_b64 s[16:17], s[0:1]
	s_cbranch_execz .LBB0_694
	v_cndmask_b32_e64 v244, v244, v239, s[8:9]
	v_cndmask_b32_e64 v245, v245, v240, s[8:9]
	v_cndmask_b32_e64 v174, v234, v174, s[6:7]
	v_cndmask_b32_e64 v175, v237, v175, s[6:7]
	s_waitcnt vmcnt(4)
	v_pk_mul_f32 v[244:245], v[126:127], v[244:245]
	v_cndmask_b32_e64 v170, v224, v170, s[6:7]
	s_waitcnt vmcnt(2)
	v_pk_fma_f32 v[174:175], v[130:131], v[174:175], v[244:245]
	v_cndmask_b32_e64 v171, v225, v171, s[6:7]
	s_waitcnt vmcnt(0)
	v_pk_fma_f32 v[154:155], v[154:155], v[134:135], v[174:175]
	v_cndmask_b32_e64 v174, v238, v228, s[8:9]
	v_cndmask_b32_e64 v175, v241, v229, s[8:9]
	v_pk_mul_f32 v[174:175], v[122:123], v[174:175]
	v_cndmask_b32_e64 v242, v242, v233, s[8:9]
	v_pk_fma_f32 v[170:171], v[114:115], v[170:171], v[174:175]
	v_cndmask_b32_e64 v243, v243, v236, s[8:9]
	v_pk_fma_f32 v[158:159], v[158:159], v[118:119], v[170:171]
	v_cndmask_b32_e64 v172, v230, v172, s[6:7]
	v_cndmask_b32_e64 v173, v231, v173, s[6:7]
	v_pk_mul_f32 v[242:243], v[124:125], v[242:243]
	v_pk_fma_f32 v[172:173], v[128:129], v[172:173], v[242:243]
	v_pk_fma_f32 v[152:153], v[152:153], v[132:133], v[172:173]
	v_cndmask_b32_e64 v172, v232, v226, s[8:9]
	v_cndmask_b32_e64 v173, v235, v227, s[8:9]
	v_pk_mul_f32 v[172:173], v[120:121], v[172:173]
	v_cndmask_b32_e64 v168, v222, v168, s[6:7]
	v_cndmask_b32_e64 v169, v223, v169, s[6:7]
	v_pk_fma_f32 v[168:169], v[112:113], v[168:169], v[172:173]
	v_pk_fma_f32 v[156:157], v[156:157], v[116:117], v[168:169]
	v_pk_mul_f32 v[168:169], v[156:157], s[98:99]
	v_pk_mul_f32 v[170:171], v[158:159], s[98:99]
	v_exp_f32_e32 v168, v168
	v_exp_f32_e32 v169, v169
	v_exp_f32_e32 v170, v170
	v_exp_f32_e32 v171, v171
	v_pk_add_f32 v[168:169], v[168:169], s[100:101]
	v_pk_add_f32 v[170:171], v[170:171], s[100:101]
	v_rcp_f32_e32 v168, v168
	v_rcp_f32_e32 v169, v169
	v_rcp_f32_e32 v170, v170
	v_rcp_f32_e32 v171, v171
	v_pk_mul_f32 v[156:157], v[156:157], v[168:169]
	v_pk_mul_f32 v[158:159], v[158:159], v[170:171]
	v_pk_mul_f32 v[152:153], v[156:157], v[152:153]
	v_pk_mul_f32 v[154:155], v[158:159], v[154:155]
	v_cvt_pk_bf16_f32 v152, v152, v153
	v_cvt_pk_bf16_f32 v153, v154, v155
	v_mov_b64_e32 v[154:155], s[30:31]
	v_mad_i64_i32 v[154:155], s[18:19], v194, s67, v[154:155]
	v_lshl_add_u64 v[154:155], v[192:193], 1, v[154:155]
	global_store_dwordx2 v[154:155], v[152:153], off
.LBB0_694:
	s_or_b64 exec, exec, s[16:17]
	v_fmamk_f32 v152, v221, 0x3a800000, v215
	v_rsq_f32_e32 v152, v152
	s_nop 0
	v_pk_fma_f32 v[150:151], v[150:151], v[152:153], v[142:143] op_sel_hi:[1,0,1]
	v_pk_fma_f32 v[148:149], v[148:149], v[152:153], v[140:141] op_sel_hi:[1,0,1]
	v_pk_fma_f32 v[146:147], v[146:147], v[152:153], v[138:139] op_sel_hi:[1,0,1]
	v_pk_fma_f32 v[144:145], v[144:145], v[152:153], v[136:137] op_sel_hi:[1,0,1]
	s_nop 1
	v_mov_b32_dpp v153, v148 row_ror:1 row_mask:0xf bank_mask:0xf
	v_mov_b32_dpp v158, v148 row_ror:2 row_mask:0xf bank_mask:0xf
	v_mov_b32_dpp v155, v149 row_ror:1 row_mask:0xf bank_mask:0xf
	v_mov_b32_dpp v159, v149 row_ror:2 row_mask:0xf bank_mask:0xf
	v_mov_b32_dpp v156, v150 row_ror:1 row_mask:0xf bank_mask:0xf
	v_mov_b32_dpp v168, v150 row_ror:2 row_mask:0xf bank_mask:0xf
	v_mov_b32_dpp v157, v151 row_ror:1 row_mask:0xf bank_mask:0xf
	v_mov_b32_dpp v169, v151 row_ror:2 row_mask:0xf bank_mask:0xf
	v_mov_b32_dpp v172, v144 row_ror:1 row_mask:0xf bank_mask:0xf
	v_mov_b32_dpp v174, v144 row_ror:2 row_mask:0xf bank_mask:0xf
	v_mov_b32_dpp v173, v145 row_ror:1 row_mask:0xf bank_mask:0xf
	v_mov_b32_dpp v221, v145 row_ror:2 row_mask:0xf bank_mask:0xf
	v_mov_b32_dpp v175, v146 row_ror:1 row_mask:0xf bank_mask:0xf
	v_mov_b32_dpp v235, v146 row_ror:2 row_mask:0xf bank_mask:0xf
	v_mov_b32_dpp v232, v147 row_ror:1 row_mask:0xf bank_mask:0xf
	v_mov_b32_dpp v238, v147 row_ror:2 row_mask:0xf bank_mask:0xf
	v_or_b32_e32 v203, 16, v200
	v_cmp_le_u32_e64 s[16:17], s46, v203
	v_add_u32_e32 v154, s41, v203
	s_and_saveexec_b64 s[18:19], s[16:17]
	s_cbranch_execz .LBB0_696
	v_cndmask_b32_e64 v170, v233, v174, s[8:9]
	v_cndmask_b32_e64 v171, v236, v221, s[8:9]
	v_cndmask_b32_e64 v230, v172, v230, s[6:7]
	v_cndmask_b32_e64 v231, v173, v231, s[6:7]
	s_waitcnt vmcnt(4)
	v_pk_mul_f32 v[170:171], v[124:125], v[170:171]
	v_cndmask_b32_e64 v224, v156, v224, s[6:7]
	s_waitcnt vmcnt(2)
	v_pk_fma_f32 v[170:171], v[128:129], v[230:231], v[170:171]
	v_cndmask_b32_e64 v225, v157, v225, s[6:7]
	s_waitcnt vmcnt(0)
	v_pk_fma_f32 v[144:145], v[144:145], v[132:133], v[170:171]
	v_cndmask_b32_e64 v170, v226, v158, s[8:9]
	v_cndmask_b32_e64 v171, v227, v159, s[8:9]
	v_cndmask_b32_e64 v226, v228, v168, s[8:9]
	v_cndmask_b32_e64 v227, v229, v169, s[8:9]
	v_pk_mul_f32 v[226:227], v[122:123], v[226:227]
	v_pk_mul_f32 v[170:171], v[120:121], v[170:171]
	v_pk_fma_f32 v[224:225], v[114:115], v[224:225], v[226:227]
	v_cndmask_b32_e64 v222, v153, v222, s[6:7]
	v_pk_fma_f32 v[150:151], v[150:151], v[118:119], v[224:225]
	v_cndmask_b32_e64 v223, v155, v223, s[6:7]
	v_pk_fma_f32 v[170:171], v[112:113], v[222:223], v[170:171]
	v_cndmask_b32_e64 v242, v239, v235, s[8:9]
	v_cndmask_b32_e64 v243, v240, v238, s[8:9]
	v_cndmask_b32_e64 v236, v175, v234, s[6:7]
	v_cndmask_b32_e64 v237, v232, v237, s[6:7]
	v_pk_mul_f32 v[240:241], v[126:127], v[242:243]
	v_pk_fma_f32 v[148:149], v[148:149], v[116:117], v[170:171]
	v_pk_fma_f32 v[236:237], v[130:131], v[236:237], v[240:241]
	v_pk_fma_f32 v[146:147], v[146:147], v[134:135], v[236:237]
	v_pk_mul_f32 v[170:171], v[148:149], s[98:99]
	v_pk_mul_f32 v[222:223], v[150:151], s[98:99]
	v_exp_f32_e32 v170, v170
	v_exp_f32_e32 v171, v171
	v_exp_f32_e32 v222, v222
	v_exp_f32_e32 v223, v223
	v_pk_add_f32 v[170:171], v[170:171], s[100:101]
	v_pk_add_f32 v[222:223], v[222:223], s[100:101]
	v_rcp_f32_e32 v170, v170
	v_rcp_f32_e32 v171, v171
	v_rcp_f32_e32 v222, v222
	v_rcp_f32_e32 v223, v223
	v_pk_mul_f32 v[148:149], v[148:149], v[170:171]
	v_pk_mul_f32 v[150:151], v[150:151], v[222:223]
	v_pk_mul_f32 v[144:145], v[148:149], v[144:145]
	v_pk_mul_f32 v[146:147], v[150:151], v[146:147]
	v_cvt_pk_bf16_f32 v144, v144, v145
	v_cvt_pk_bf16_f32 v145, v146, v147
	v_mov_b64_e32 v[146:147], s[30:31]
	v_mad_i64_i32 v[146:147], s[20:21], v154, s67, v[146:147]
	v_lshl_add_u64 v[146:147], v[192:193], 1, v[146:147]
	global_store_dwordx2 v[146:147], v[144:145], off
.LBB0_696:
	s_or_b64 exec, exec, s[18:19]
	v_fmamk_f32 v144, v220, 0x3a800000, v215
	v_rsq_f32_e32 v144, v144
	s_nop 0
	v_pk_fma_f32 v[110:111], v[110:111], v[144:145], v[142:143] op_sel_hi:[1,0,1]
	v_pk_fma_f32 v[108:109], v[108:109], v[144:145], v[140:141] op_sel_hi:[1,0,1]
	v_pk_fma_f32 v[102:103], v[102:103], v[144:145], v[138:139] op_sel_hi:[1,0,1]
	v_pk_fma_f32 v[100:101], v[100:101], v[144:145], v[136:137] op_sel_hi:[1,0,1]
	s_nop 1
	v_mov_b32_dpp v145, v108 row_ror:1 row_mask:0xf bank_mask:0xf
	v_mov_b32_dpp v150, v108 row_ror:2 row_mask:0xf bank_mask:0xf
	v_mov_b32_dpp v146, v109 row_ror:1 row_mask:0xf bank_mask:0xf
	v_mov_b32_dpp v151, v109 row_ror:2 row_mask:0xf bank_mask:0xf
	v_mov_b32_dpp v148, v110 row_ror:1 row_mask:0xf bank_mask:0xf
	v_mov_b32_dpp v170, v110 row_ror:2 row_mask:0xf bank_mask:0xf
	v_mov_b32_dpp v149, v111 row_ror:1 row_mask:0xf bank_mask:0xf
	v_mov_b32_dpp v171, v111 row_ror:2 row_mask:0xf bank_mask:0xf
	v_mov_b32_dpp v220, v100 row_ror:1 row_mask:0xf bank_mask:0xf
	v_mov_b32_dpp v223, v100 row_ror:2 row_mask:0xf bank_mask:0xf
	v_mov_b32_dpp v222, v101 row_ror:1 row_mask:0xf bank_mask:0xf
	v_mov_b32_dpp v225, v101 row_ror:2 row_mask:0xf bank_mask:0xf
	v_mov_b32_dpp v224, v102 row_ror:1 row_mask:0xf bank_mask:0xf
	v_mov_b32_dpp v227, v102 row_ror:2 row_mask:0xf bank_mask:0xf
	v_mov_b32_dpp v226, v103 row_ror:1 row_mask:0xf bank_mask:0xf
	v_mov_b32_dpp v228, v103 row_ror:2 row_mask:0xf bank_mask:0xf
	v_or_b32_e32 v204, 32, v200
	v_cmp_le_u32_e64 s[18:19], s46, v204
	v_add_u32_e32 v147, s41, v204
	s_and_saveexec_b64 s[20:21], s[18:19]
	s_cbranch_execz .LBB0_698
	v_cndmask_b32_e64 v168, v168, v170, s[8:9]
	v_cndmask_b32_e64 v169, v169, v171, s[8:9]
	s_waitcnt vmcnt(5)
	v_pk_mul_f32 v[168:169], v[122:123], v[168:169]
	v_cndmask_b32_e64 v156, v148, v156, s[6:7]
	v_cndmask_b32_e64 v157, v149, v157, s[6:7]
	s_waitcnt vmcnt(3)
	v_pk_fma_f32 v[156:157], v[114:115], v[156:157], v[168:169]
	v_cndmask_b32_e64 v234, v235, v227, s[8:9]
	s_waitcnt vmcnt(1)
	v_pk_fma_f32 v[110:111], v[110:111], v[118:119], v[156:157]
	v_cndmask_b32_e64 v157, v146, v155, s[6:7]
	v_cndmask_b32_e64 v156, v145, v153, s[6:7]
	v_cndmask_b32_e64 v235, v238, v228, s[8:9]
	v_cndmask_b32_e64 v158, v158, v150, s[8:9]
	v_cndmask_b32_e64 v159, v159, v151, s[8:9]
	v_cndmask_b32_e64 v230, v174, v223, s[8:9]
	v_cndmask_b32_e64 v174, v224, v175, s[6:7]
	v_cndmask_b32_e64 v175, v226, v232, s[6:7]
	v_pk_mul_f32 v[232:233], v[126:127], v[234:235]
	v_pk_mul_f32 v[158:159], v[120:121], v[158:159]
	v_pk_fma_f32 v[174:175], v[130:131], v[174:175], v[232:233]
	v_pk_fma_f32 v[156:157], v[112:113], v[156:157], v[158:159]
	s_waitcnt vmcnt(0)
	v_pk_fma_f32 v[102:103], v[102:103], v[134:135], v[174:175]
	v_pk_fma_f32 v[108:109], v[108:109], v[116:117], v[156:157]
	v_cndmask_b32_e64 v231, v221, v225, s[8:9]
	v_cndmask_b32_e64 v172, v220, v172, s[6:7]
	v_cndmask_b32_e64 v173, v222, v173, s[6:7]
	v_pk_mul_f32 v[230:231], v[124:125], v[230:231]
	v_pk_fma_f32 v[172:173], v[128:129], v[172:173], v[230:231]
	v_pk_fma_f32 v[100:101], v[100:101], v[132:133], v[172:173]
	v_pk_mul_f32 v[156:157], v[108:109], s[98:99]
	v_pk_mul_f32 v[158:159], v[110:111], s[98:99]
	v_exp_f32_e32 v156, v156
	v_exp_f32_e32 v157, v157
	v_exp_f32_e32 v158, v158
	v_exp_f32_e32 v159, v159
	v_pk_add_f32 v[156:157], v[156:157], s[100:101]
	v_pk_add_f32 v[158:159], v[158:159], s[100:101]
	v_rcp_f32_e32 v156, v156
	v_rcp_f32_e32 v157, v157
	v_rcp_f32_e32 v158, v158
	v_rcp_f32_e32 v159, v159
	v_pk_mul_f32 v[108:109], v[108:109], v[156:157]
	v_pk_mul_f32 v[110:111], v[110:111], v[158:159]
	v_pk_mul_f32 v[100:101], v[108:109], v[100:101]
	v_pk_mul_f32 v[102:103], v[110:111], v[102:103]
	v_cvt_pk_bf16_f32 v100, v100, v101
	v_cvt_pk_bf16_f32 v101, v102, v103
	v_mov_b64_e32 v[102:103], s[30:31]
	v_mad_i64_i32 v[102:103], s[22:23], v147, s67, v[102:103]
	v_lshl_add_u64 v[102:103], v[192:193], 1, v[102:103]
	global_store_dwordx2 v[102:103], v[100:101], off
.LBB0_698:
	s_or_b64 exec, exec, s[20:21]
	s_nop 1
	v_mov_b32_dpp v100, v160 row_ror:1 row_mask:0xf bank_mask:0xf
	v_mov_b32_dpp v108, v160 row_ror:2 row_mask:0xf bank_mask:0xf
	v_mov_b32_dpp v101, v161 row_ror:1 row_mask:0xf bank_mask:0xf
	v_mov_b32_dpp v110, v161 row_ror:2 row_mask:0xf bank_mask:0xf
	v_mov_b32_dpp v102, v162 row_ror:1 row_mask:0xf bank_mask:0xf
	v_mov_b32_dpp v111, v162 row_ror:2 row_mask:0xf bank_mask:0xf
	v_mov_b32_dpp v103, v163 row_ror:1 row_mask:0xf bank_mask:0xf
	v_mov_b32_dpp v153, v163 row_ror:2 row_mask:0xf bank_mask:0xf
	v_mov_b32_dpp v155, v164 row_ror:1 row_mask:0xf bank_mask:0xf
	v_mov_b32_dpp v157, v164 row_ror:2 row_mask:0xf bank_mask:0xf
	v_mov_b32_dpp v156, v165 row_ror:1 row_mask:0xf bank_mask:0xf
	v_mov_b32_dpp v159, v165 row_ror:2 row_mask:0xf bank_mask:0xf
	v_mov_b32_dpp v158, v166 row_ror:1 row_mask:0xf bank_mask:0xf
	v_mov_b32_dpp v169, v166 row_ror:2 row_mask:0xf bank_mask:0xf
	v_mov_b32_dpp v168, v167 row_ror:1 row_mask:0xf bank_mask:0xf
	v_mov_b32_dpp v172, v167 row_ror:2 row_mask:0xf bank_mask:0xf
	v_or_b32_e32 v205, 48, v200
	v_cmp_le_u32_e64 s[20:21], s46, v205
	v_add_u32_e32 v109, s41, v205
	s_and_saveexec_b64 s[22:23], s[20:21]
	s_cbranch_execz .LBB0_700
	v_cndmask_b32_e64 v151, v151, v110, s[8:9]
	v_cndmask_b32_e64 v110, v170, v111, s[8:9]
	v_cndmask_b32_e64 v111, v171, v153, s[8:9]
	s_waitcnt vmcnt(5)
	v_pk_mul_f32 v[110:111], v[122:123], v[110:111]
	v_cndmask_b32_e64 v102, v102, v148, s[6:7]
	v_cndmask_b32_e64 v103, v103, v149, s[6:7]
	s_waitcnt vmcnt(3)
	v_pk_fma_f32 v[102:103], v[114:115], v[102:103], v[110:111]
	v_cndmask_b32_e64 v150, v150, v108, s[8:9]
	s_waitcnt vmcnt(1)
	v_pk_fma_f32 v[102:103], v[162:163], v[118:119], v[102:103]
	v_pk_mul_f32 v[150:151], v[120:121], v[150:151]
	v_cndmask_b32_e64 v100, v100, v145, s[6:7]
	v_cndmask_b32_e64 v101, v101, v146, s[6:7]
	v_pk_fma_f32 v[100:101], v[112:113], v[100:101], v[150:151]
	v_cndmask_b32_e64 v174, v223, v157, s[8:9]
	v_pk_fma_f32 v[100:101], v[160:161], v[116:117], v[100:101]
	v_cndmask_b32_e64 v175, v225, v159, s[8:9]
	v_cndmask_b32_e64 v230, v227, v169, s[8:9]
	v_cndmask_b32_e64 v231, v228, v172, s[8:9]
	v_cndmask_b32_e64 v172, v155, v220, s[6:7]
	v_cndmask_b32_e64 v173, v156, v222, s[6:7]
	v_cndmask_b32_e64 v156, v158, v224, s[6:7]
	v_cndmask_b32_e64 v157, v168, v226, s[6:7]
	v_pk_mul_f32 v[158:159], v[124:125], v[174:175]
	v_pk_mul_f32 v[168:169], v[126:127], v[230:231]
	v_pk_fma_f32 v[158:159], v[128:129], v[172:173], v[158:159]
	v_pk_fma_f32 v[156:157], v[130:131], v[156:157], v[168:169]
	s_waitcnt vmcnt(0)
	v_pk_fma_f32 v[158:159], v[164:165], v[132:133], v[158:159]
	v_pk_fma_f32 v[156:157], v[166:167], v[134:135], v[156:157]
	v_pk_mul_f32 v[110:111], v[100:101], s[98:99]
	v_pk_mul_f32 v[150:151], v[102:103], s[98:99]
	v_exp_f32_e32 v110, v110
	v_exp_f32_e32 v111, v111
	v_exp_f32_e32 v150, v150
	v_exp_f32_e32 v151, v151
	v_pk_add_f32 v[110:111], v[110:111], s[100:101]
	v_pk_add_f32 v[150:151], v[150:151], s[100:101]
	v_rcp_f32_e32 v110, v110
	v_rcp_f32_e32 v111, v111
	v_rcp_f32_e32 v150, v150
	v_rcp_f32_e32 v151, v151
	v_pk_mul_f32 v[100:101], v[100:101], v[110:111]
	v_pk_mul_f32 v[102:103], v[102:103], v[150:151]
	v_pk_mul_f32 v[100:101], v[100:101], v[158:159]
	v_pk_mul_f32 v[102:103], v[102:103], v[156:157]
	v_cvt_pk_bf16_f32 v100, v100, v101
	v_cvt_pk_bf16_f32 v101, v102, v103
	v_mov_b64_e32 v[102:103], s[30:31]
	v_mad_i64_i32 v[102:103], s[24:25], v109, s67, v[102:103]
	v_lshl_add_u64 v[102:103], v[192:193], 1, v[102:103]
	global_store_dwordx2 v[102:103], v[100:101], off
.LBB0_700:
	s_or_b64 exec, exec, s[22:23]
	v_fmamk_f32 v100, v219, 0x3a800000, v215
	v_rsq_f32_e32 v108, v100
	s_nop 0
	v_pk_fma_f32 v[94:95], v[94:95], v[108:109], v[142:143] op_sel_hi:[1,0,1]
	v_pk_fma_f32 v[92:93], v[92:93], v[108:109], v[140:141] op_sel_hi:[1,0,1]
	v_pk_fma_f32 v[90:91], v[90:91], v[108:109], v[138:139] op_sel_hi:[1,0,1]
	v_pk_fma_f32 v[88:89], v[88:89], v[108:109], v[136:137] op_sel_hi:[1,0,1]
	s_nop 1
	v_mov_b32_dpp v100, v92 row_ror:1 row_mask:0xf bank_mask:0xf
	v_mov_b32_dpp v110, v92 row_ror:2 row_mask:0xf bank_mask:0xf
	v_mov_b32_dpp v101, v93 row_ror:1 row_mask:0xf bank_mask:0xf
	v_mov_b32_dpp v145, v93 row_ror:2 row_mask:0xf bank_mask:0xf
	v_mov_b32_dpp v102, v94 row_ror:1 row_mask:0xf bank_mask:0xf
	v_mov_b32_dpp v150, v94 row_ror:2 row_mask:0xf bank_mask:0xf
	v_mov_b32_dpp v103, v95 row_ror:1 row_mask:0xf bank_mask:0xf
	v_mov_b32_dpp v151, v95 row_ror:2 row_mask:0xf bank_mask:0xf
	v_mov_b32_dpp v153, v88 row_ror:1 row_mask:0xf bank_mask:0xf
	v_mov_b32_dpp v156, v88 row_ror:2 row_mask:0xf bank_mask:0xf
	v_mov_b32_dpp v155, v89 row_ror:1 row_mask:0xf bank_mask:0xf
	v_mov_b32_dpp v158, v89 row_ror:2 row_mask:0xf bank_mask:0xf
	v_mov_b32_dpp v157, v90 row_ror:1 row_mask:0xf bank_mask:0xf
	v_mov_b32_dpp v160, v90 row_ror:2 row_mask:0xf bank_mask:0xf
	v_mov_b32_dpp v159, v91 row_ror:1 row_mask:0xf bank_mask:0xf
	v_mov_b32_dpp v161, v91 row_ror:2 row_mask:0xf bank_mask:0xf
	v_add_u32_e32 v206, 0x80, v200
	v_cmp_le_u32_e64 s[22:23], s46, v206
	v_add_u32_e32 v149, s64, v202
	v_add_u32_e32 v111, s41, v206
	s_and_saveexec_b64 s[24:25], s[22:23]
	s_cbranch_execz .LBB0_702
	ds_read_b128 v[162:165], v149 offset:288
	ds_read_b128 v[166:169], v149 offset:32
	ds_read_b128 v[170:173], v149
	ds_read_b128 v[220:223], v149 offset:256
	s_waitcnt lgkmcnt(2)
	v_cndmask_b32_e64 v146, v165, v169, s[6:7]
	v_cndmask_b32_e64 v148, v164, v168, s[6:7]
	v_cndmask_b32_e64 v168, v148, v160, s[8:9]
	v_cndmask_b32_e64 v169, v146, v161, s[8:9]
	v_cndmask_b32_e64 v167, v163, v167, s[6:7]
	v_cndmask_b32_e64 v166, v162, v166, s[6:7]
	v_cndmask_b32_e64 v164, v157, v164, s[6:7]
	v_cndmask_b32_e64 v165, v159, v165, s[6:7]
	s_waitcnt vmcnt(4)
	v_pk_mul_f32 v[168:169], v[126:127], v[168:169]
	v_cndmask_b32_e64 v166, v166, v156, s[8:9]
	v_cndmask_b32_e64 v167, v167, v158, s[8:9]
	s_waitcnt vmcnt(2)
	v_pk_fma_f32 v[164:165], v[130:131], v[164:165], v[168:169]
	s_waitcnt lgkmcnt(0)
	v_cndmask_b32_e64 v146, v223, v173, s[6:7]
	v_cndmask_b32_e64 v148, v222, v172, s[6:7]
	v_cndmask_b32_e64 v162, v153, v162, s[6:7]
	v_cndmask_b32_e64 v163, v155, v163, s[6:7]
	v_pk_mul_f32 v[166:167], v[124:125], v[166:167]
	s_waitcnt vmcnt(0)
	v_pk_fma_f32 v[90:91], v[90:91], v[134:135], v[164:165]
	v_cndmask_b32_e64 v164, v148, v150, s[8:9]
	v_cndmask_b32_e64 v165, v146, v151, s[8:9]
	v_pk_fma_f32 v[162:163], v[128:129], v[162:163], v[166:167]
	v_pk_mul_f32 v[164:165], v[122:123], v[164:165]
	v_cndmask_b32_e64 v166, v102, v222, s[6:7]
	v_cndmask_b32_e64 v167, v103, v223, s[6:7]
	v_pk_fma_f32 v[164:165], v[114:115], v[166:167], v[164:165]
	v_pk_fma_f32 v[88:89], v[88:89], v[132:133], v[162:163]
	v_pk_fma_f32 v[94:95], v[94:95], v[118:119], v[164:165]
	v_cndmask_b32_e64 v163, v221, v171, s[6:7]
	v_cndmask_b32_e64 v162, v220, v170, s[6:7]
	v_cndmask_b32_e64 v162, v162, v110, s[8:9]
	v_cndmask_b32_e64 v163, v163, v145, s[8:9]
	v_pk_mul_f32 v[162:163], v[120:121], v[162:163]
	v_cndmask_b32_e64 v164, v100, v220, s[6:7]
	v_cndmask_b32_e64 v165, v101, v221, s[6:7]
	v_pk_fma_f32 v[162:163], v[112:113], v[164:165], v[162:163]
	v_pk_fma_f32 v[92:93], v[92:93], v[116:117], v[162:163]
	v_pk_mul_f32 v[162:163], v[92:93], s[98:99]
	v_pk_mul_f32 v[164:165], v[94:95], s[98:99]
	v_exp_f32_e32 v162, v162
	v_exp_f32_e32 v163, v163
	v_exp_f32_e32 v164, v164
	v_exp_f32_e32 v165, v165
	v_pk_add_f32 v[162:163], v[162:163], s[100:101]
	v_pk_add_f32 v[164:165], v[164:165], s[100:101]
	v_rcp_f32_e32 v162, v162
	v_rcp_f32_e32 v163, v163
	v_rcp_f32_e32 v164, v164
	v_rcp_f32_e32 v165, v165
	v_pk_mul_f32 v[92:93], v[92:93], v[162:163]
	v_pk_mul_f32 v[94:95], v[94:95], v[164:165]
	v_pk_mul_f32 v[88:89], v[92:93], v[88:89]
	v_pk_mul_f32 v[90:91], v[94:95], v[90:91]
	v_cvt_pk_bf16_f32 v88, v88, v89
	v_cvt_pk_bf16_f32 v89, v90, v91
	v_mov_b64_e32 v[90:91], s[30:31]
	v_mad_i64_i32 v[90:91], s[26:27], v111, s67, v[90:91]
	v_lshl_add_u64 v[90:91], v[192:193], 1, v[90:91]
	global_store_dwordx2 v[90:91], v[88:89], off
.LBB0_702:
	s_or_b64 exec, exec, s[24:25]
	v_fmamk_f32 v88, v218, 0x3a800000, v215
	v_rsq_f32_e32 v146, v88
	s_nop 0
	v_pk_fma_f32 v[86:87], v[86:87], v[146:147], v[142:143] op_sel_hi:[1,0,1]
	v_pk_fma_f32 v[84:85], v[84:85], v[146:147], v[140:141] op_sel_hi:[1,0,1]
	v_pk_fma_f32 v[82:83], v[82:83], v[146:147], v[138:139] op_sel_hi:[1,0,1]
	v_pk_fma_f32 v[80:81], v[80:81], v[146:147], v[136:137] op_sel_hi:[1,0,1]
	s_nop 1
	v_mov_b32_dpp v88, v84 row_ror:1 row_mask:0xf bank_mask:0xf
	v_mov_b32_dpp v92, v84 row_ror:2 row_mask:0xf bank_mask:0xf
	v_mov_b32_dpp v89, v85 row_ror:1 row_mask:0xf bank_mask:0xf
	v_mov_b32_dpp v93, v85 row_ror:2 row_mask:0xf bank_mask:0xf
	v_mov_b32_dpp v90, v86 row_ror:1 row_mask:0xf bank_mask:0xf
	v_mov_b32_dpp v94, v86 row_ror:2 row_mask:0xf bank_mask:0xf
	v_mov_b32_dpp v91, v87 row_ror:1 row_mask:0xf bank_mask:0xf
	v_mov_b32_dpp v95, v87 row_ror:2 row_mask:0xf bank_mask:0xf
	v_mov_b32_dpp v162, v80 row_ror:1 row_mask:0xf bank_mask:0xf
	v_mov_b32_dpp v164, v80 row_ror:2 row_mask:0xf bank_mask:0xf
	v_mov_b32_dpp v163, v81 row_ror:1 row_mask:0xf bank_mask:0xf
	v_mov_b32_dpp v166, v81 row_ror:2 row_mask:0xf bank_mask:0xf
	v_mov_b32_dpp v165, v82 row_ror:1 row_mask:0xf bank_mask:0xf
	v_mov_b32_dpp v168, v82 row_ror:2 row_mask:0xf bank_mask:0xf
	v_mov_b32_dpp v167, v83 row_ror:1 row_mask:0xf bank_mask:0xf
	v_mov_b32_dpp v169, v83 row_ror:2 row_mask:0xf bank_mask:0xf
	v_add_u32_e32 v207, 0x90, v200
	v_cmp_le_u32_e64 s[24:25], s46, v207
	v_add_u32_e32 v148, s41, v207
	s_and_saveexec_b64 s[26:27], s[24:25]
	s_cbranch_execz .LBB0_704
	v_cndmask_b32_e64 v150, v150, v94, s[8:9]
	v_cndmask_b32_e64 v151, v151, v95, s[8:9]
	s_waitcnt vmcnt(5)
	v_pk_mul_f32 v[150:151], v[122:123], v[150:151]
	v_cndmask_b32_e64 v102, v90, v102, s[6:7]
	v_cndmask_b32_e64 v103, v91, v103, s[6:7]
	s_waitcnt vmcnt(3)
	v_pk_fma_f32 v[102:103], v[114:115], v[102:103], v[150:151]
	v_cndmask_b32_e64 v160, v160, v168, s[8:9]
	s_waitcnt vmcnt(1)
	v_pk_fma_f32 v[86:87], v[86:87], v[118:119], v[102:103]
	v_cndmask_b32_e64 v161, v161, v169, s[8:9]
	v_cndmask_b32_e64 v170, v156, v164, s[8:9]
	v_cndmask_b32_e64 v156, v165, v157, s[6:7]
	v_cndmask_b32_e64 v157, v167, v159, s[6:7]
	v_pk_mul_f32 v[160:161], v[126:127], v[160:161]
	v_pk_fma_f32 v[156:157], v[130:131], v[156:157], v[160:161]
	s_waitcnt vmcnt(0)
	v_pk_fma_f32 v[82:83], v[82:83], v[134:135], v[156:157]
	v_cndmask_b32_e64 v156, v110, v92, s[8:9]
	v_cndmask_b32_e64 v157, v145, v93, s[8:9]
	v_pk_mul_f32 v[156:157], v[120:121], v[156:157]
	v_cndmask_b32_e64 v100, v88, v100, s[6:7]
	v_cndmask_b32_e64 v101, v89, v101, s[6:7]
	v_pk_fma_f32 v[100:101], v[112:113], v[100:101], v[156:157]
	v_pk_fma_f32 v[84:85], v[84:85], v[116:117], v[100:101]
	v_cndmask_b32_e64 v171, v158, v166, s[8:9]
	v_cndmask_b32_e64 v172, v162, v153, s[6:7]
	v_cndmask_b32_e64 v173, v163, v155, s[6:7]
	v_pk_mul_f32 v[158:159], v[124:125], v[170:171]
	v_pk_fma_f32 v[158:159], v[128:129], v[172:173], v[158:159]
	v_pk_fma_f32 v[80:81], v[80:81], v[132:133], v[158:159]
	v_pk_mul_f32 v[100:101], v[84:85], s[98:99]
	v_pk_mul_f32 v[102:103], v[86:87], s[98:99]
	v_exp_f32_e32 v100, v100
	v_exp_f32_e32 v101, v101
	v_exp_f32_e32 v102, v102
	v_exp_f32_e32 v103, v103
	v_pk_add_f32 v[100:101], v[100:101], s[100:101]
	v_pk_add_f32 v[102:103], v[102:103], s[100:101]
	v_rcp_f32_e32 v100, v100
	v_rcp_f32_e32 v101, v101
	v_rcp_f32_e32 v102, v102
	v_rcp_f32_e32 v103, v103
	v_pk_mul_f32 v[84:85], v[84:85], v[100:101]
	v_pk_mul_f32 v[86:87], v[86:87], v[102:103]
	v_pk_mul_f32 v[80:81], v[84:85], v[80:81]
	v_pk_mul_f32 v[82:83], v[86:87], v[82:83]
	v_cvt_pk_bf16_f32 v80, v80, v81
	v_cvt_pk_bf16_f32 v81, v82, v83
	v_mov_b64_e32 v[82:83], s[30:31]
	v_mad_i64_i32 v[82:83], s[28:29], v148, s67, v[82:83]
	v_lshl_add_u64 v[82:83], v[192:193], 1, v[82:83]
	global_store_dwordx2 v[82:83], v[80:81], off
.LBB0_704:
	s_or_b64 exec, exec, s[26:27]
	v_fmamk_f32 v80, v199, 0x3a800000, v215
	v_rsq_f32_e32 v110, v80
	s_nop 0
	v_pk_fma_f32 v[78:79], v[78:79], v[110:111], v[142:143] op_sel_hi:[1,0,1]
	v_pk_fma_f32 v[76:77], v[76:77], v[110:111], v[140:141] op_sel_hi:[1,0,1]
	v_pk_fma_f32 v[74:75], v[74:75], v[110:111], v[138:139] op_sel_hi:[1,0,1]
	v_pk_fma_f32 v[72:73], v[72:73], v[110:111], v[136:137] op_sel_hi:[1,0,1]
	s_nop 1
	v_mov_b32_dpp v80, v76 row_ror:1 row_mask:0xf bank_mask:0xf
	v_mov_b32_dpp v84, v76 row_ror:2 row_mask:0xf bank_mask:0xf
	v_mov_b32_dpp v81, v77 row_ror:1 row_mask:0xf bank_mask:0xf
	v_mov_b32_dpp v85, v77 row_ror:2 row_mask:0xf bank_mask:0xf
	v_mov_b32_dpp v82, v78 row_ror:1 row_mask:0xf bank_mask:0xf
	v_mov_b32_dpp v86, v78 row_ror:2 row_mask:0xf bank_mask:0xf
	v_mov_b32_dpp v83, v79 row_ror:1 row_mask:0xf bank_mask:0xf
	v_mov_b32_dpp v87, v79 row_ror:2 row_mask:0xf bank_mask:0xf
	v_mov_b32_dpp v100, v72 row_ror:1 row_mask:0xf bank_mask:0xf
	v_mov_b32_dpp v102, v72 row_ror:2 row_mask:0xf bank_mask:0xf
	v_mov_b32_dpp v101, v73 row_ror:1 row_mask:0xf bank_mask:0xf
	v_mov_b32_dpp v138, v73 row_ror:2 row_mask:0xf bank_mask:0xf
	v_mov_b32_dpp v103, v74 row_ror:1 row_mask:0xf bank_mask:0xf
	v_mov_b32_dpp v140, v74 row_ror:2 row_mask:0xf bank_mask:0xf
	v_mov_b32_dpp v139, v75 row_ror:1 row_mask:0xf bank_mask:0xf
	v_mov_b32_dpp v141, v75 row_ror:2 row_mask:0xf bank_mask:0xf
	v_add_u32_e32 v209, 0xa0, v200
	v_cmp_le_u32_e64 s[26:27], s46, v209
	v_add_u32_e32 v136, s41, v209
	s_and_saveexec_b64 s[28:29], s[26:27]
	s_cbranch_execz .LBB0_706
	v_cndmask_b32_e64 v94, v94, v86, s[8:9]
	v_cndmask_b32_e64 v95, v95, v87, s[8:9]
	s_waitcnt vmcnt(5)
	v_pk_mul_f32 v[94:95], v[122:123], v[94:95]
	v_cndmask_b32_e64 v90, v82, v90, s[6:7]
	v_cndmask_b32_e64 v91, v83, v91, s[6:7]
	s_waitcnt vmcnt(3)
	v_pk_fma_f32 v[90:91], v[114:115], v[90:91], v[94:95]
	v_cndmask_b32_e64 v150, v168, v140, s[8:9]
	s_waitcnt vmcnt(1)
	v_pk_fma_f32 v[78:79], v[78:79], v[118:119], v[90:91]
	v_cndmask_b32_e64 v151, v169, v141, s[8:9]
	v_cndmask_b32_e64 v92, v92, v84, s[8:9]
	v_cndmask_b32_e64 v93, v93, v85, s[8:9]
	v_cndmask_b32_e64 v158, v103, v165, s[6:7]
	v_cndmask_b32_e64 v159, v139, v167, s[6:7]
	v_pk_mul_f32 v[150:151], v[126:127], v[150:151]
	v_pk_mul_f32 v[92:93], v[120:121], v[92:93]
	v_cndmask_b32_e64 v88, v80, v88, s[6:7]
	v_cndmask_b32_e64 v89, v81, v89, s[6:7]
	v_pk_fma_f32 v[150:151], v[130:131], v[158:159], v[150:151]
	v_pk_fma_f32 v[88:89], v[112:113], v[88:89], v[92:93]
	s_waitcnt vmcnt(0)
	v_pk_fma_f32 v[74:75], v[74:75], v[134:135], v[150:151]
	v_pk_fma_f32 v[76:77], v[76:77], v[116:117], v[88:89]
	v_cndmask_b32_e64 v142, v164, v102, s[8:9]
	v_cndmask_b32_e64 v143, v166, v138, s[8:9]
	v_cndmask_b32_e64 v156, v100, v162, s[6:7]
	v_cndmask_b32_e64 v157, v101, v163, s[6:7]
	v_pk_mul_f32 v[142:143], v[124:125], v[142:143]
	v_pk_fma_f32 v[142:143], v[128:129], v[156:157], v[142:143]
	v_pk_fma_f32 v[72:73], v[72:73], v[132:133], v[142:143]
	v_pk_mul_f32 v[88:89], v[76:77], s[98:99]
	v_pk_mul_f32 v[90:91], v[78:79], s[98:99]
	v_exp_f32_e32 v88, v88
	v_exp_f32_e32 v89, v89
	v_exp_f32_e32 v90, v90
	v_exp_f32_e32 v91, v91
	v_pk_add_f32 v[88:89], v[88:89], s[100:101]
	v_pk_add_f32 v[90:91], v[90:91], s[100:101]
	v_rcp_f32_e32 v88, v88
	v_rcp_f32_e32 v89, v89
	v_rcp_f32_e32 v90, v90
	v_rcp_f32_e32 v91, v91
	v_pk_mul_f32 v[76:77], v[76:77], v[88:89]
	v_pk_mul_f32 v[78:79], v[78:79], v[90:91]
	v_pk_mul_f32 v[72:73], v[76:77], v[72:73]
	v_pk_mul_f32 v[74:75], v[78:79], v[74:75]
	v_cvt_pk_bf16_f32 v72, v72, v73
	v_cvt_pk_bf16_f32 v73, v74, v75
	v_mov_b64_e32 v[74:75], s[30:31]
	v_mad_i64_i32 v[74:75], s[70:71], v136, s67, v[74:75]
	v_lshl_add_u64 v[74:75], v[192:193], 1, v[74:75]
	global_store_dwordx2 v[74:75], v[72:73], off
.LBB0_706:
	s_or_b64 exec, exec, s[28:29]
	s_nop 1
	v_mov_b32_dpp v72, v96 row_ror:1 row_mask:0xf bank_mask:0xf
	v_mov_b32_dpp v76, v96 row_ror:2 row_mask:0xf bank_mask:0xf
	v_mov_b32_dpp v73, v97 row_ror:1 row_mask:0xf bank_mask:0xf
	v_mov_b32_dpp v77, v97 row_ror:2 row_mask:0xf bank_mask:0xf
	v_mov_b32_dpp v74, v98 row_ror:1 row_mask:0xf bank_mask:0xf
	v_mov_b32_dpp v78, v98 row_ror:2 row_mask:0xf bank_mask:0xf
	v_mov_b32_dpp v75, v99 row_ror:1 row_mask:0xf bank_mask:0xf
	v_mov_b32_dpp v79, v99 row_ror:2 row_mask:0xf bank_mask:0xf
	v_mov_b32_dpp v88, v104 row_ror:1 row_mask:0xf bank_mask:0xf
	v_mov_b32_dpp v90, v104 row_ror:2 row_mask:0xf bank_mask:0xf
	v_mov_b32_dpp v89, v105 row_ror:1 row_mask:0xf bank_mask:0xf
	v_mov_b32_dpp v92, v105 row_ror:2 row_mask:0xf bank_mask:0xf
	v_mov_b32_dpp v91, v106 row_ror:1 row_mask:0xf bank_mask:0xf
	v_mov_b32_dpp v94, v106 row_ror:2 row_mask:0xf bank_mask:0xf
	v_mov_b32_dpp v93, v107 row_ror:1 row_mask:0xf bank_mask:0xf
	v_mov_b32_dpp v95, v107 row_ror:2 row_mask:0xf bank_mask:0xf
	v_add_u32_e32 v210, 0xb0, v200
	v_cmp_le_u32_e64 s[28:29], s46, v210
	v_add_u32_e32 v137, s41, v210
	s_and_saveexec_b64 s[46:47], s[28:29]
	s_cbranch_execz .LBB0_708
	v_cndmask_b32_e64 v78, v86, v78, s[8:9]
	v_cndmask_b32_e64 v79, v87, v79, s[8:9]
	s_waitcnt vmcnt(5)
	v_pk_mul_f32 v[78:79], v[122:123], v[78:79]
	v_cndmask_b32_e64 v74, v74, v82, s[6:7]
	v_cndmask_b32_e64 v75, v75, v83, s[6:7]
	s_waitcnt vmcnt(3)
	v_pk_fma_f32 v[74:75], v[114:115], v[74:75], v[78:79]
	v_cndmask_b32_e64 v76, v84, v76, s[8:9]
	s_waitcnt vmcnt(1)
	v_pk_fma_f32 v[74:75], v[98:99], v[118:119], v[74:75]
	v_cndmask_b32_e64 v77, v85, v77, s[8:9]
	v_pk_mul_f32 v[76:77], v[120:121], v[76:77]
	v_cndmask_b32_e64 v72, v72, v80, s[6:7]
	v_cndmask_b32_e64 v73, v73, v81, s[6:7]
	v_pk_fma_f32 v[72:73], v[112:113], v[72:73], v[76:77]
	v_pk_fma_f32 v[72:73], v[96:97], v[116:117], v[72:73]
	v_cndmask_b32_e64 v142, v102, v90, s[8:9]
	v_cndmask_b32_e64 v143, v138, v92, s[8:9]
	v_cndmask_b32_e64 v94, v140, v94, s[8:9]
	v_cndmask_b32_e64 v95, v141, v95, s[8:9]
	v_cndmask_b32_e64 v88, v88, v100, s[6:7]
	v_cndmask_b32_e64 v89, v89, v101, s[6:7]
	v_cndmask_b32_e64 v90, v91, v103, s[6:7]
	v_cndmask_b32_e64 v91, v93, v139, s[6:7]
	v_pk_mul_f32 v[92:93], v[124:125], v[142:143]
	v_pk_mul_f32 v[94:95], v[126:127], v[94:95]
	v_pk_fma_f32 v[88:89], v[128:129], v[88:89], v[92:93]
	v_pk_fma_f32 v[90:91], v[130:131], v[90:91], v[94:95]
	s_waitcnt vmcnt(0)
	v_pk_fma_f32 v[88:89], v[104:105], v[132:133], v[88:89]
	v_pk_fma_f32 v[90:91], v[106:107], v[134:135], v[90:91]
	v_pk_mul_f32 v[76:77], v[72:73], s[98:99]
	v_pk_mul_f32 v[78:79], v[74:75], s[98:99]
	v_exp_f32_e32 v76, v76
	v_exp_f32_e32 v77, v77
	v_exp_f32_e32 v78, v78
	v_exp_f32_e32 v79, v79
	v_pk_add_f32 v[76:77], v[76:77], s[100:101]
	v_pk_add_f32 v[78:79], v[78:79], s[100:101]
	v_rcp_f32_e32 v76, v76
	v_rcp_f32_e32 v77, v77
	v_rcp_f32_e32 v78, v78
	v_rcp_f32_e32 v79, v79
	v_pk_mul_f32 v[72:73], v[72:73], v[76:77]
	v_pk_mul_f32 v[74:75], v[74:75], v[78:79]
	v_pk_mul_f32 v[72:73], v[72:73], v[88:89]
	v_pk_mul_f32 v[74:75], v[74:75], v[90:91]
	v_cvt_pk_bf16_f32 v72, v72, v73
	v_cvt_pk_bf16_f32 v73, v74, v75
	v_mov_b64_e32 v[74:75], s[30:31]
	v_mad_i64_i32 v[74:75], s[70:71], v137, s67, v[74:75]
	v_lshl_add_u64 v[74:75], v[192:193], 1, v[74:75]
	global_store_dwordx2 v[74:75], v[72:73], off

.LBB0_710:
	v_mov_b32_e32 v199, v198
	v_mov_b32_e32 v104, v198
	v_mov_b32_e32 v105, v198
	v_pk_fma_f32 v[62:63], v[62:63], v[104:105], v[46:47]
	v_pk_fma_f32 v[60:61], v[60:61], v[198:199], v[44:45]
	v_pk_fma_f32 v[58:59], v[58:59], v[104:105], v[42:43]
	v_pk_fma_f32 v[56:57], v[56:57], v[198:199], v[40:41]
	s_waitcnt vmcnt(7)
	s_nop 1
	v_mov_b32_dpp v104, v60 row_ror:1 row_mask:0xf bank_mask:0xf
	v_mov_b32_dpp v112, v60 row_ror:2 row_mask:0xf bank_mask:0xf
	v_mov_b32_dpp v105, v61 row_ror:1 row_mask:0xf bank_mask:0xf
	v_mov_b32_dpp v113, v61 row_ror:2 row_mask:0xf bank_mask:0xf
	v_mov_b32_dpp v106, v62 row_ror:1 row_mask:0xf bank_mask:0xf
	v_mov_b32_dpp v114, v62 row_ror:2 row_mask:0xf bank_mask:0xf
	v_mov_b32_dpp v107, v63 row_ror:1 row_mask:0xf bank_mask:0xf
	v_mov_b32_dpp v115, v63 row_ror:2 row_mask:0xf bank_mask:0xf
	v_mov_b32_dpp v116, v56 row_ror:1 row_mask:0xf bank_mask:0xf
	v_mov_b32_dpp v118, v56 row_ror:2 row_mask:0xf bank_mask:0xf
	v_mov_b32_dpp v117, v57 row_ror:1 row_mask:0xf bank_mask:0xf
	v_mov_b32_dpp v120, v57 row_ror:2 row_mask:0xf bank_mask:0xf
	v_mov_b32_dpp v119, v58 row_ror:1 row_mask:0xf bank_mask:0xf
	v_mov_b32_dpp v122, v58 row_ror:2 row_mask:0xf bank_mask:0xf
	v_mov_b32_dpp v121, v59 row_ror:1 row_mask:0xf bank_mask:0xf
	v_mov_b32_dpp v123, v59 row_ror:2 row_mask:0xf bank_mask:0xf
	s_and_saveexec_b64 s[46:47], s[0:1]
	s_cbranch_execz .LBB0_712
	v_cndmask_b32_e64 v130, v130, v122, s[8:9]
	v_cndmask_b32_e64 v131, v131, v123, s[8:9]
	v_cndmask_b32_e64 v102, v119, v102, s[6:7]
	v_cndmask_b32_e64 v103, v121, v103, s[6:7]
	s_waitcnt vmcnt(4)
	v_pk_mul_f32 v[130:131], v[86:87], v[130:131]
	v_cndmask_b32_e64 v98, v106, v98, s[6:7]
	s_waitcnt vmcnt(2)
	v_pk_fma_f32 v[102:103], v[90:91], v[102:103], v[130:131]
	v_cndmask_b32_e64 v99, v107, v99, s[6:7]
	s_waitcnt vmcnt(0)
	v_pk_fma_f32 v[58:59], v[58:59], v[94:95], v[102:103]
	v_cndmask_b32_e64 v102, v126, v114, s[8:9]
	v_cndmask_b32_e64 v103, v127, v115, s[8:9]
	v_pk_mul_f32 v[102:103], v[78:79], v[102:103]
	v_cndmask_b32_e64 v128, v128, v118, s[8:9]
	v_pk_fma_f32 v[98:99], v[74:75], v[98:99], v[102:103]
	v_cndmask_b32_e64 v129, v129, v120, s[8:9]
	v_pk_fma_f32 v[62:63], v[62:63], v[82:83], v[98:99]
	v_cndmask_b32_e64 v100, v116, v100, s[6:7]
	v_cndmask_b32_e64 v101, v117, v101, s[6:7]
	v_pk_mul_f32 v[128:129], v[84:85], v[128:129]
	v_pk_fma_f32 v[100:101], v[88:89], v[100:101], v[128:129]
	v_pk_fma_f32 v[56:57], v[56:57], v[92:93], v[100:101]
	v_cndmask_b32_e64 v100, v124, v112, s[8:9]
	v_cndmask_b32_e64 v101, v125, v113, s[8:9]
	v_pk_mul_f32 v[100:101], v[76:77], v[100:101]
	v_cndmask_b32_e64 v96, v104, v96, s[6:7]
	v_cndmask_b32_e64 v97, v105, v97, s[6:7]
	v_pk_fma_f32 v[96:97], v[72:73], v[96:97], v[100:101]
	v_pk_fma_f32 v[60:61], v[60:61], v[80:81], v[96:97]
	v_pk_mul_f32 v[96:97], v[60:61], s[98:99]
	v_pk_mul_f32 v[98:99], v[62:63], s[98:99]
	v_exp_f32_e32 v96, v96
	v_exp_f32_e32 v97, v97
	v_exp_f32_e32 v98, v98
	v_exp_f32_e32 v99, v99
	v_pk_add_f32 v[96:97], v[96:97], s[100:101]
	v_pk_add_f32 v[98:99], v[98:99], s[100:101]
	v_rcp_f32_e32 v96, v96
	v_rcp_f32_e32 v97, v97
	v_rcp_f32_e32 v98, v98
	v_rcp_f32_e32 v99, v99
	v_pk_mul_f32 v[60:61], v[60:61], v[96:97]
	v_pk_mul_f32 v[62:63], v[62:63], v[98:99]
	v_pk_mul_f32 v[56:57], v[60:61], v[56:57]
	v_pk_mul_f32 v[58:59], v[62:63], v[58:59]
	v_cvt_pk_bf16_f32 v56, v56, v57
	v_cvt_pk_bf16_f32 v57, v58, v59
	v_mov_b64_e32 v[58:59], s[30:31]
	v_mad_i64_i32 v[58:59], s[0:1], v194, s67, v[58:59]
	v_lshl_add_u64 v[58:59], v[192:193], 1, v[58:59]
	global_store_dwordx2 v[58:59], v[56:57], off offset:8
.LBB0_712:
	s_or_b64 exec, exec, s[46:47]
	v_mov_b32_e32 v153, v152
	v_mov_b32_e32 v56, v152
	v_mov_b32_e32 v57, v152
	v_pk_fma_f32 v[54:55], v[54:55], v[56:57], v[46:47]
	v_pk_fma_f32 v[52:53], v[52:53], v[152:153], v[44:45]
	v_pk_fma_f32 v[50:51], v[50:51], v[56:57], v[42:43]
	v_pk_fma_f32 v[48:49], v[48:49], v[152:153], v[40:41]
	s_nop 1
	v_mov_b32_dpp v56, v52 row_ror:1 row_mask:0xf bank_mask:0xf
	v_mov_b32_dpp v60, v52 row_ror:2 row_mask:0xf bank_mask:0xf
	v_mov_b32_dpp v57, v53 row_ror:1 row_mask:0xf bank_mask:0xf
	v_mov_b32_dpp v61, v53 row_ror:2 row_mask:0xf bank_mask:0xf
	v_mov_b32_dpp v58, v54 row_ror:1 row_mask:0xf bank_mask:0xf
	v_mov_b32_dpp v62, v54 row_ror:2 row_mask:0xf bank_mask:0xf
	v_mov_b32_dpp v59, v55 row_ror:1 row_mask:0xf bank_mask:0xf
	v_mov_b32_dpp v63, v55 row_ror:2 row_mask:0xf bank_mask:0xf
	v_mov_b32_dpp v96, v48 row_ror:1 row_mask:0xf bank_mask:0xf
	v_mov_b32_dpp v98, v48 row_ror:2 row_mask:0xf bank_mask:0xf
	v_mov_b32_dpp v97, v49 row_ror:1 row_mask:0xf bank_mask:0xf
	v_mov_b32_dpp v100, v49 row_ror:2 row_mask:0xf bank_mask:0xf
	v_mov_b32_dpp v99, v50 row_ror:1 row_mask:0xf bank_mask:0xf
	v_mov_b32_dpp v102, v50 row_ror:2 row_mask:0xf bank_mask:0xf
	v_mov_b32_dpp v101, v51 row_ror:1 row_mask:0xf bank_mask:0xf
	v_mov_b32_dpp v103, v51 row_ror:2 row_mask:0xf bank_mask:0xf
	s_and_saveexec_b64 s[0:1], s[16:17]
	s_cbranch_execz .LBB0_714
	v_cndmask_b32_e64 v114, v114, v62, s[8:9]
	v_cndmask_b32_e64 v115, v115, v63, s[8:9]
	s_waitcnt vmcnt(5)
	v_pk_mul_f32 v[114:115], v[78:79], v[114:115]
	v_cndmask_b32_e64 v106, v58, v106, s[6:7]
	v_cndmask_b32_e64 v107, v59, v107, s[6:7]
	s_waitcnt vmcnt(3)
	v_pk_fma_f32 v[106:107], v[74:75], v[106:107], v[114:115]
	v_cndmask_b32_e64 v122, v122, v102, s[8:9]
	s_waitcnt vmcnt(1)
	v_pk_fma_f32 v[54:55], v[54:55], v[82:83], v[106:107]
	v_cndmask_b32_e64 v123, v123, v103, s[8:9]
	v_cndmask_b32_e64 v112, v112, v60, s[8:9]
	v_cndmask_b32_e64 v113, v113, v61, s[8:9]
	v_cndmask_b32_e64 v124, v118, v98, s[8:9]
	v_cndmask_b32_e64 v118, v99, v119, s[6:7]
	v_cndmask_b32_e64 v119, v101, v121, s[6:7]
	v_pk_mul_f32 v[122:123], v[86:87], v[122:123]
	v_pk_mul_f32 v[112:113], v[76:77], v[112:113]
	v_cndmask_b32_e64 v104, v56, v104, s[6:7]
	v_cndmask_b32_e64 v105, v57, v105, s[6:7]
	v_pk_fma_f32 v[118:119], v[90:91], v[118:119], v[122:123]
	v_pk_fma_f32 v[104:105], v[72:73], v[104:105], v[112:113]
	s_waitcnt vmcnt(0)
	v_pk_fma_f32 v[50:51], v[50:51], v[94:95], v[118:119]
	v_pk_fma_f32 v[52:53], v[52:53], v[80:81], v[104:105]
	v_cndmask_b32_e64 v125, v120, v100, s[8:9]
	v_cndmask_b32_e64 v116, v96, v116, s[6:7]
	v_cndmask_b32_e64 v117, v97, v117, s[6:7]
	v_pk_mul_f32 v[120:121], v[84:85], v[124:125]
	v_pk_fma_f32 v[116:117], v[88:89], v[116:117], v[120:121]
	v_pk_fma_f32 v[48:49], v[48:49], v[92:93], v[116:117]
	v_pk_mul_f32 v[104:105], v[52:53], s[98:99]
	v_pk_mul_f32 v[106:107], v[54:55], s[98:99]
	v_exp_f32_e32 v104, v104
	v_exp_f32_e32 v105, v105
	v_exp_f32_e32 v106, v106
	v_exp_f32_e32 v107, v107
	v_pk_add_f32 v[104:105], v[104:105], s[100:101]
	v_pk_add_f32 v[106:107], v[106:107], s[100:101]
	v_rcp_f32_e32 v104, v104
	v_rcp_f32_e32 v105, v105
	v_rcp_f32_e32 v106, v106
	v_rcp_f32_e32 v107, v107
	v_pk_mul_f32 v[52:53], v[52:53], v[104:105]
	v_pk_mul_f32 v[54:55], v[54:55], v[106:107]
	v_pk_mul_f32 v[48:49], v[52:53], v[48:49]
	v_pk_mul_f32 v[50:51], v[54:55], v[50:51]
	v_cvt_pk_bf16_f32 v48, v48, v49
	v_cvt_pk_bf16_f32 v49, v50, v51
	v_mov_b64_e32 v[50:51], s[30:31]
	v_mad_i64_i32 v[50:51], s[16:17], v154, s67, v[50:51]
	v_lshl_add_u64 v[50:51], v[192:193], 1, v[50:51]
	global_store_dwordx2 v[50:51], v[48:49], off offset:8
.LBB0_714:
	s_or_b64 exec, exec, s[0:1]
	v_mov_b32_e32 v145, v144
	v_mov_b32_e32 v48, v144
	v_mov_b32_e32 v49, v144
	v_pk_fma_f32 v[34:35], v[34:35], v[48:49], v[46:47]
	v_pk_fma_f32 v[32:33], v[32:33], v[144:145], v[44:45]
	v_pk_fma_f32 v[30:31], v[30:31], v[48:49], v[42:43]
	v_pk_fma_f32 v[28:29], v[28:29], v[144:145], v[40:41]
	s_nop 1
	v_mov_b32_dpp v48, v32 row_ror:1 row_mask:0xf bank_mask:0xf
	v_mov_b32_dpp v52, v32 row_ror:2 row_mask:0xf bank_mask:0xf
	v_mov_b32_dpp v49, v33 row_ror:1 row_mask:0xf bank_mask:0xf
	v_mov_b32_dpp v53, v33 row_ror:2 row_mask:0xf bank_mask:0xf
	v_mov_b32_dpp v50, v34 row_ror:1 row_mask:0xf bank_mask:0xf
	v_mov_b32_dpp v54, v34 row_ror:2 row_mask:0xf bank_mask:0xf
	v_mov_b32_dpp v51, v35 row_ror:1 row_mask:0xf bank_mask:0xf
	v_mov_b32_dpp v55, v35 row_ror:2 row_mask:0xf bank_mask:0xf
	v_mov_b32_dpp v104, v28 row_ror:1 row_mask:0xf bank_mask:0xf
	v_mov_b32_dpp v106, v28 row_ror:2 row_mask:0xf bank_mask:0xf
	v_mov_b32_dpp v105, v29 row_ror:1 row_mask:0xf bank_mask:0xf
	v_mov_b32_dpp v112, v29 row_ror:2 row_mask:0xf bank_mask:0xf
	v_mov_b32_dpp v107, v30 row_ror:1 row_mask:0xf bank_mask:0xf
	v_mov_b32_dpp v114, v30 row_ror:2 row_mask:0xf bank_mask:0xf
	v_mov_b32_dpp v113, v31 row_ror:1 row_mask:0xf bank_mask:0xf
	v_mov_b32_dpp v115, v31 row_ror:2 row_mask:0xf bank_mask:0xf
	s_and_saveexec_b64 s[0:1], s[18:19]
	s_cbranch_execz .LBB0_716
	v_cndmask_b32_e64 v62, v62, v54, s[8:9]
	v_cndmask_b32_e64 v63, v63, v55, s[8:9]
	s_waitcnt vmcnt(5)
	v_pk_mul_f32 v[62:63], v[78:79], v[62:63]
	v_cndmask_b32_e64 v58, v50, v58, s[6:7]
	v_cndmask_b32_e64 v59, v51, v59, s[6:7]
	s_waitcnt vmcnt(3)
	v_pk_fma_f32 v[58:59], v[74:75], v[58:59], v[62:63]
	v_cndmask_b32_e64 v102, v102, v114, s[8:9]
	s_waitcnt vmcnt(1)
	v_pk_fma_f32 v[34:35], v[34:35], v[82:83], v[58:59]
	v_cndmask_b32_e64 v103, v103, v115, s[8:9]
	v_cndmask_b32_e64 v60, v60, v52, s[8:9]
	v_cndmask_b32_e64 v61, v61, v53, s[8:9]
	v_cndmask_b32_e64 v116, v98, v106, s[8:9]
	v_cndmask_b32_e64 v98, v107, v99, s[6:7]
	v_cndmask_b32_e64 v99, v113, v101, s[6:7]
	v_pk_mul_f32 v[102:103], v[86:87], v[102:103]
	v_pk_mul_f32 v[60:61], v[76:77], v[60:61]
	v_cndmask_b32_e64 v56, v48, v56, s[6:7]
	v_cndmask_b32_e64 v57, v49, v57, s[6:7]
	v_pk_fma_f32 v[98:99], v[90:91], v[98:99], v[102:103]
	v_pk_fma_f32 v[56:57], v[72:73], v[56:57], v[60:61]
	s_waitcnt vmcnt(0)
	v_pk_fma_f32 v[30:31], v[30:31], v[94:95], v[98:99]
	v_pk_fma_f32 v[32:33], v[32:33], v[80:81], v[56:57]
	v_cndmask_b32_e64 v117, v100, v112, s[8:9]
	v_cndmask_b32_e64 v96, v104, v96, s[6:7]
	v_cndmask_b32_e64 v97, v105, v97, s[6:7]
	v_pk_mul_f32 v[100:101], v[84:85], v[116:117]
	v_pk_fma_f32 v[96:97], v[88:89], v[96:97], v[100:101]
	v_pk_fma_f32 v[28:29], v[28:29], v[92:93], v[96:97]
	v_pk_mul_f32 v[56:57], v[32:33], s[98:99]
	v_pk_mul_f32 v[58:59], v[34:35], s[98:99]
	v_exp_f32_e32 v56, v56
	v_exp_f32_e32 v57, v57
	v_exp_f32_e32 v58, v58
	v_exp_f32_e32 v59, v59
	v_pk_add_f32 v[56:57], v[56:57], s[100:101]
	v_pk_add_f32 v[58:59], v[58:59], s[100:101]
	v_rcp_f32_e32 v56, v56
	v_rcp_f32_e32 v57, v57
	v_rcp_f32_e32 v58, v58
	v_rcp_f32_e32 v59, v59
	v_pk_mul_f32 v[32:33], v[32:33], v[56:57]
	v_pk_mul_f32 v[34:35], v[34:35], v[58:59]
	v_pk_mul_f32 v[28:29], v[32:33], v[28:29]
	v_pk_mul_f32 v[30:31], v[34:35], v[30:31]
	v_cvt_pk_bf16_f32 v28, v28, v29
	v_cvt_pk_bf16_f32 v29, v30, v31
	v_mov_b64_e32 v[30:31], s[30:31]
	v_mad_i64_i32 v[30:31], s[16:17], v147, s67, v[30:31]
	v_lshl_add_u64 v[30:31], v[192:193], 1, v[30:31]
	global_store_dwordx2 v[30:31], v[28:29], off offset:8
.LBB0_716:
	s_or_b64 exec, exec, s[0:1]
	s_nop 1
	v_mov_b32_dpp v28, v64 row_ror:1 row_mask:0xf bank_mask:0xf
	v_mov_b32_dpp v32, v64 row_ror:2 row_mask:0xf bank_mask:0xf
	v_mov_b32_dpp v29, v65 row_ror:1 row_mask:0xf bank_mask:0xf
	v_mov_b32_dpp v33, v65 row_ror:2 row_mask:0xf bank_mask:0xf
	v_mov_b32_dpp v30, v66 row_ror:1 row_mask:0xf bank_mask:0xf
	v_mov_b32_dpp v34, v66 row_ror:2 row_mask:0xf bank_mask:0xf
	v_mov_b32_dpp v31, v67 row_ror:1 row_mask:0xf bank_mask:0xf
	v_mov_b32_dpp v35, v67 row_ror:2 row_mask:0xf bank_mask:0xf
	v_mov_b32_dpp v56, v68 row_ror:1 row_mask:0xf bank_mask:0xf
	v_mov_b32_dpp v58, v68 row_ror:2 row_mask:0xf bank_mask:0xf
	v_mov_b32_dpp v57, v69 row_ror:1 row_mask:0xf bank_mask:0xf
	v_mov_b32_dpp v60, v69 row_ror:2 row_mask:0xf bank_mask:0xf
	v_mov_b32_dpp v59, v70 row_ror:1 row_mask:0xf bank_mask:0xf
	v_mov_b32_dpp v62, v70 row_ror:2 row_mask:0xf bank_mask:0xf
	v_mov_b32_dpp v61, v71 row_ror:1 row_mask:0xf bank_mask:0xf
	v_mov_b32_dpp v63, v71 row_ror:2 row_mask:0xf bank_mask:0xf
	s_and_saveexec_b64 s[0:1], s[20:21]
	s_cbranch_execz .LBB0_718
	v_cndmask_b32_e64 v34, v54, v34, s[8:9]
	v_cndmask_b32_e64 v35, v55, v35, s[8:9]
	s_waitcnt vmcnt(5)
	v_pk_mul_f32 v[34:35], v[78:79], v[34:35]
	v_cndmask_b32_e64 v30, v30, v50, s[6:7]
	v_cndmask_b32_e64 v31, v31, v51, s[6:7]
	s_waitcnt vmcnt(3)
	v_pk_fma_f32 v[30:31], v[74:75], v[30:31], v[34:35]
	v_cndmask_b32_e64 v32, v52, v32, s[8:9]
	s_waitcnt vmcnt(1)
	v_pk_fma_f32 v[30:31], v[66:67], v[82:83], v[30:31]
	v_cndmask_b32_e64 v33, v53, v33, s[8:9]
	v_pk_mul_f32 v[32:33], v[76:77], v[32:33]
	v_cndmask_b32_e64 v28, v28, v48, s[6:7]
	v_cndmask_b32_e64 v29, v29, v49, s[6:7]
	v_pk_fma_f32 v[28:29], v[72:73], v[28:29], v[32:33]
	v_pk_fma_f32 v[28:29], v[64:65], v[80:81], v[28:29]
	v_cndmask_b32_e64 v96, v106, v58, s[8:9]
	v_cndmask_b32_e64 v97, v112, v60, s[8:9]
	v_cndmask_b32_e64 v62, v114, v62, s[8:9]
	v_cndmask_b32_e64 v63, v115, v63, s[8:9]
	v_cndmask_b32_e64 v56, v56, v104, s[6:7]
	v_cndmask_b32_e64 v57, v57, v105, s[6:7]
	v_cndmask_b32_e64 v58, v59, v107, s[6:7]
	v_cndmask_b32_e64 v59, v61, v113, s[6:7]
	v_pk_mul_f32 v[60:61], v[84:85], v[96:97]
	v_pk_mul_f32 v[62:63], v[86:87], v[62:63]
	v_pk_fma_f32 v[56:57], v[88:89], v[56:57], v[60:61]
	v_pk_fma_f32 v[58:59], v[90:91], v[58:59], v[62:63]
	s_waitcnt vmcnt(0)
	v_pk_fma_f32 v[56:57], v[68:69], v[92:93], v[56:57]
	v_pk_fma_f32 v[58:59], v[70:71], v[94:95], v[58:59]
	v_pk_mul_f32 v[32:33], v[28:29], s[98:99]
	v_pk_mul_f32 v[34:35], v[30:31], s[98:99]
	v_exp_f32_e32 v32, v32
	v_exp_f32_e32 v33, v33
	v_exp_f32_e32 v34, v34
	v_exp_f32_e32 v35, v35
	v_pk_add_f32 v[32:33], v[32:33], s[100:101]
	v_pk_add_f32 v[34:35], v[34:35], s[100:101]
	v_rcp_f32_e32 v32, v32
	v_rcp_f32_e32 v33, v33
	v_rcp_f32_e32 v34, v34
	v_rcp_f32_e32 v35, v35
	v_pk_mul_f32 v[28:29], v[28:29], v[32:33]
	v_pk_mul_f32 v[30:31], v[30:31], v[34:35]
	v_pk_mul_f32 v[28:29], v[28:29], v[56:57]
	v_pk_mul_f32 v[30:31], v[30:31], v[58:59]
	v_cvt_pk_bf16_f32 v28, v28, v29
	v_cvt_pk_bf16_f32 v29, v30, v31
	v_mov_b64_e32 v[30:31], s[30:31]
	v_mad_i64_i32 v[30:31], s[16:17], v109, s67, v[30:31]
	v_lshl_add_u64 v[30:31], v[192:193], 1, v[30:31]
	global_store_dwordx2 v[30:31], v[28:29], off offset:8
.LBB0_718:
	s_or_b64 exec, exec, s[0:1]
	v_mov_b32_e32 v109, v108
	v_mov_b32_e32 v28, v108
	v_mov_b32_e32 v29, v108
	v_pk_fma_f32 v[22:23], v[22:23], v[28:29], v[46:47]
	v_pk_fma_f32 v[20:21], v[20:21], v[108:109], v[44:45]
	v_pk_fma_f32 v[18:19], v[18:19], v[28:29], v[42:43]
	v_pk_fma_f32 v[16:17], v[16:17], v[108:109], v[40:41]
	s_nop 1
	v_mov_b32_dpp v28, v20 row_ror:1 row_mask:0xf bank_mask:0xf
	v_mov_b32_dpp v32, v20 row_ror:2 row_mask:0xf bank_mask:0xf
	v_mov_b32_dpp v29, v21 row_ror:1 row_mask:0xf bank_mask:0xf
	v_mov_b32_dpp v33, v21 row_ror:2 row_mask:0xf bank_mask:0xf
	v_mov_b32_dpp v30, v22 row_ror:1 row_mask:0xf bank_mask:0xf
	v_mov_b32_dpp v34, v22 row_ror:2 row_mask:0xf bank_mask:0xf
	v_mov_b32_dpp v31, v23 row_ror:1 row_mask:0xf bank_mask:0xf
	v_mov_b32_dpp v35, v23 row_ror:2 row_mask:0xf bank_mask:0xf
	v_mov_b32_dpp v48, v16 row_ror:1 row_mask:0xf bank_mask:0xf
	v_mov_b32_dpp v50, v16 row_ror:2 row_mask:0xf bank_mask:0xf
	v_mov_b32_dpp v49, v17 row_ror:1 row_mask:0xf bank_mask:0xf
	v_mov_b32_dpp v52, v17 row_ror:2 row_mask:0xf bank_mask:0xf
	v_mov_b32_dpp v51, v18 row_ror:1 row_mask:0xf bank_mask:0xf
	v_mov_b32_dpp v54, v18 row_ror:2 row_mask:0xf bank_mask:0xf
	v_mov_b32_dpp v53, v19 row_ror:1 row_mask:0xf bank_mask:0xf
	v_mov_b32_dpp v55, v19 row_ror:2 row_mask:0xf bank_mask:0xf
	s_and_saveexec_b64 s[0:1], s[22:23]
	s_cbranch_execz .LBB0_720
	ds_read_b128 v[56:59], v149 offset:304
	ds_read_b128 v[60:63], v149 offset:48
	ds_read_b128 v[64:67], v149 offset:16
	ds_read_b128 v[68:71], v149 offset:272
	s_waitcnt lgkmcnt(2)
	v_cndmask_b32_e64 v63, v59, v63, s[6:7]
	v_cndmask_b32_e64 v62, v58, v62, s[6:7]
	v_cndmask_b32_e64 v62, v62, v54, s[8:9]
	v_cndmask_b32_e64 v63, v63, v55, s[8:9]
	v_cndmask_b32_e64 v58, v51, v58, s[6:7]
	v_cndmask_b32_e64 v59, v53, v59, s[6:7]
	s_waitcnt vmcnt(4)
	v_pk_mul_f32 v[62:63], v[86:87], v[62:63]
	v_cndmask_b32_e64 v61, v57, v61, s[6:7]
	v_cndmask_b32_e64 v60, v56, v60, s[6:7]
	s_waitcnt vmcnt(2)
	v_pk_fma_f32 v[58:59], v[90:91], v[58:59], v[62:63]
	v_cndmask_b32_e64 v60, v60, v50, s[8:9]
	v_cndmask_b32_e64 v61, v61, v52, s[8:9]
	s_waitcnt vmcnt(0)
	v_pk_fma_f32 v[18:19], v[18:19], v[94:95], v[58:59]
	s_waitcnt lgkmcnt(0)
	v_cndmask_b32_e64 v59, v71, v67, s[6:7]
	v_cndmask_b32_e64 v58, v70, v66, s[6:7]
	v_cndmask_b32_e64 v56, v48, v56, s[6:7]
	v_cndmask_b32_e64 v57, v49, v57, s[6:7]
	v_pk_mul_f32 v[60:61], v[84:85], v[60:61]
	v_cndmask_b32_e64 v58, v58, v34, s[8:9]
	v_cndmask_b32_e64 v59, v59, v35, s[8:9]
	v_pk_fma_f32 v[56:57], v[88:89], v[56:57], v[60:61]
	v_pk_mul_f32 v[58:59], v[78:79], v[58:59]
	v_cndmask_b32_e64 v60, v30, v70, s[6:7]
	v_cndmask_b32_e64 v61, v31, v71, s[6:7]
	v_pk_fma_f32 v[58:59], v[74:75], v[60:61], v[58:59]
	v_pk_fma_f32 v[16:17], v[16:17], v[92:93], v[56:57]
	v_pk_fma_f32 v[22:23], v[22:23], v[82:83], v[58:59]
	v_cndmask_b32_e64 v57, v69, v65, s[6:7]
	v_cndmask_b32_e64 v56, v68, v64, s[6:7]
	v_cndmask_b32_e64 v56, v56, v32, s[8:9]
	v_cndmask_b32_e64 v57, v57, v33, s[8:9]
	v_pk_mul_f32 v[56:57], v[76:77], v[56:57]
	v_cndmask_b32_e64 v58, v28, v68, s[6:7]
	v_cndmask_b32_e64 v59, v29, v69, s[6:7]
	v_pk_fma_f32 v[56:57], v[72:73], v[58:59], v[56:57]
	v_pk_fma_f32 v[20:21], v[20:21], v[80:81], v[56:57]
	v_pk_mul_f32 v[56:57], v[20:21], s[98:99]
	v_pk_mul_f32 v[58:59], v[22:23], s[98:99]
	v_exp_f32_e32 v56, v56
	v_exp_f32_e32 v57, v57
	v_exp_f32_e32 v58, v58
	v_exp_f32_e32 v59, v59
	v_pk_add_f32 v[56:57], v[56:57], s[100:101]
	v_pk_add_f32 v[58:59], v[58:59], s[100:101]
	v_rcp_f32_e32 v56, v56
	v_rcp_f32_e32 v57, v57
	v_rcp_f32_e32 v58, v58
	v_rcp_f32_e32 v59, v59
	v_pk_mul_f32 v[20:21], v[20:21], v[56:57]
	v_pk_mul_f32 v[22:23], v[22:23], v[58:59]
	v_pk_mul_f32 v[16:17], v[20:21], v[16:17]
	v_pk_mul_f32 v[18:19], v[22:23], v[18:19]
	v_cvt_pk_bf16_f32 v16, v16, v17
	v_cvt_pk_bf16_f32 v17, v18, v19
	v_mov_b64_e32 v[18:19], s[30:31]
	v_mad_i64_i32 v[18:19], s[16:17], v111, s67, v[18:19]
	v_lshl_add_u64 v[18:19], v[192:193], 1, v[18:19]
	global_store_dwordx2 v[18:19], v[16:17], off offset:8
.LBB0_720:
	s_or_b64 exec, exec, s[0:1]
	v_mov_b32_e32 v147, v146
	v_mov_b32_e32 v16, v146
	v_mov_b32_e32 v17, v146
	v_pk_fma_f32 v[14:15], v[14:15], v[16:17], v[46:47]
	v_pk_fma_f32 v[12:13], v[12:13], v[146:147], v[44:45]
	v_pk_fma_f32 v[10:11], v[10:11], v[16:17], v[42:43]
	v_pk_fma_f32 v[8:9], v[8:9], v[146:147], v[40:41]
	s_nop 1
	v_mov_b32_dpp v16, v12 row_ror:1 row_mask:0xf bank_mask:0xf
	v_mov_b32_dpp v20, v12 row_ror:2 row_mask:0xf bank_mask:0xf
	v_mov_b32_dpp v17, v13 row_ror:1 row_mask:0xf bank_mask:0xf
	v_mov_b32_dpp v21, v13 row_ror:2 row_mask:0xf bank_mask:0xf
	v_mov_b32_dpp v18, v14 row_ror:1 row_mask:0xf bank_mask:0xf
	v_mov_b32_dpp v22, v14 row_ror:2 row_mask:0xf bank_mask:0xf
	v_mov_b32_dpp v19, v15 row_ror:1 row_mask:0xf bank_mask:0xf
	v_mov_b32_dpp v23, v15 row_ror:2 row_mask:0xf bank_mask:0xf
	v_mov_b32_dpp v56, v8 row_ror:1 row_mask:0xf bank_mask:0xf
	v_mov_b32_dpp v58, v8 row_ror:2 row_mask:0xf bank_mask:0xf
	v_mov_b32_dpp v57, v9 row_ror:1 row_mask:0xf bank_mask:0xf
	v_mov_b32_dpp v60, v9 row_ror:2 row_mask:0xf bank_mask:0xf
	v_mov_b32_dpp v59, v10 row_ror:1 row_mask:0xf bank_mask:0xf
	v_mov_b32_dpp v62, v10 row_ror:2 row_mask:0xf bank_mask:0xf
	v_mov_b32_dpp v61, v11 row_ror:1 row_mask:0xf bank_mask:0xf
	v_mov_b32_dpp v63, v11 row_ror:2 row_mask:0xf bank_mask:0xf
	s_and_saveexec_b64 s[0:1], s[24:25]
	s_cbranch_execz .LBB0_722
	v_cndmask_b32_e64 v34, v34, v22, s[8:9]
	v_cndmask_b32_e64 v35, v35, v23, s[8:9]
	s_waitcnt vmcnt(5)
	v_pk_mul_f32 v[34:35], v[78:79], v[34:35]
	v_cndmask_b32_e64 v30, v18, v30, s[6:7]
	v_cndmask_b32_e64 v31, v19, v31, s[6:7]
	s_waitcnt vmcnt(3)
	v_pk_fma_f32 v[30:31], v[74:75], v[30:31], v[34:35]
	v_cndmask_b32_e64 v54, v54, v62, s[8:9]
	s_waitcnt vmcnt(1)
	v_pk_fma_f32 v[14:15], v[14:15], v[82:83], v[30:31]
	v_cndmask_b32_e64 v55, v55, v63, s[8:9]
	v_cndmask_b32_e64 v32, v32, v20, s[8:9]
	v_cndmask_b32_e64 v33, v33, v21, s[8:9]
	v_cndmask_b32_e64 v64, v50, v58, s[8:9]
	v_cndmask_b32_e64 v50, v59, v51, s[6:7]
	v_cndmask_b32_e64 v51, v61, v53, s[6:7]
	v_pk_mul_f32 v[54:55], v[86:87], v[54:55]
	v_pk_mul_f32 v[32:33], v[76:77], v[32:33]
	v_cndmask_b32_e64 v28, v16, v28, s[6:7]
	v_cndmask_b32_e64 v29, v17, v29, s[6:7]
	v_pk_fma_f32 v[50:51], v[90:91], v[50:51], v[54:55]
	v_pk_fma_f32 v[28:29], v[72:73], v[28:29], v[32:33]
	s_waitcnt vmcnt(0)
	v_pk_fma_f32 v[10:11], v[10:11], v[94:95], v[50:51]
	v_pk_fma_f32 v[12:13], v[12:13], v[80:81], v[28:29]
	v_cndmask_b32_e64 v65, v52, v60, s[8:9]
	v_cndmask_b32_e64 v48, v56, v48, s[6:7]
	v_cndmask_b32_e64 v49, v57, v49, s[6:7]
	v_pk_mul_f32 v[52:53], v[84:85], v[64:65]
	v_pk_fma_f32 v[48:49], v[88:89], v[48:49], v[52:53]
	v_pk_fma_f32 v[8:9], v[8:9], v[92:93], v[48:49]
	v_pk_mul_f32 v[28:29], v[12:13], s[98:99]
	v_pk_mul_f32 v[30:31], v[14:15], s[98:99]
	v_exp_f32_e32 v28, v28
	v_exp_f32_e32 v29, v29
	v_exp_f32_e32 v30, v30
	v_exp_f32_e32 v31, v31
	v_pk_add_f32 v[28:29], v[28:29], s[100:101]
	v_pk_add_f32 v[30:31], v[30:31], s[100:101]
	v_rcp_f32_e32 v28, v28
	v_rcp_f32_e32 v29, v29
	v_rcp_f32_e32 v30, v30
	v_rcp_f32_e32 v31, v31
	v_pk_mul_f32 v[12:13], v[12:13], v[28:29]
	v_pk_mul_f32 v[14:15], v[14:15], v[30:31]
	v_pk_mul_f32 v[8:9], v[12:13], v[8:9]
	v_pk_mul_f32 v[10:11], v[14:15], v[10:11]
	v_cvt_pk_bf16_f32 v8, v8, v9
	v_cvt_pk_bf16_f32 v9, v10, v11
	v_mov_b64_e32 v[10:11], s[30:31]
	v_mad_i64_i32 v[10:11], s[16:17], v148, s67, v[10:11]
	v_lshl_add_u64 v[10:11], v[192:193], 1, v[10:11]
	global_store_dwordx2 v[10:11], v[8:9], off offset:8
.LBB0_722:
	s_or_b64 exec, exec, s[0:1]
	v_mov_b32_e32 v111, v110
	v_mov_b32_e32 v8, v110
	v_mov_b32_e32 v9, v110
	v_pk_fma_f32 v[6:7], v[6:7], v[8:9], v[46:47]
	v_pk_fma_f32 v[4:5], v[4:5], v[110:111], v[44:45]
	v_pk_fma_f32 v[2:3], v[2:3], v[8:9], v[42:43]
	v_pk_fma_f32 v[0:1], v[0:1], v[110:111], v[40:41]
	s_nop 1
	v_mov_b32_dpp v8, v4 row_ror:1 row_mask:0xf bank_mask:0xf
	v_mov_b32_dpp v12, v4 row_ror:2 row_mask:0xf bank_mask:0xf
	v_mov_b32_dpp v9, v5 row_ror:1 row_mask:0xf bank_mask:0xf
	v_mov_b32_dpp v13, v5 row_ror:2 row_mask:0xf bank_mask:0xf
	v_mov_b32_dpp v10, v6 row_ror:1 row_mask:0xf bank_mask:0xf
	v_mov_b32_dpp v14, v6 row_ror:2 row_mask:0xf bank_mask:0xf
	v_mov_b32_dpp v11, v7 row_ror:1 row_mask:0xf bank_mask:0xf
	v_mov_b32_dpp v15, v7 row_ror:2 row_mask:0xf bank_mask:0xf
	v_mov_b32_dpp v28, v0 row_ror:1 row_mask:0xf bank_mask:0xf
	v_mov_b32_dpp v32, v0 row_ror:2 row_mask:0xf bank_mask:0xf
	v_mov_b32_dpp v29, v1 row_ror:1 row_mask:0xf bank_mask:0xf
	v_mov_b32_dpp v33, v1 row_ror:2 row_mask:0xf bank_mask:0xf
	v_mov_b32_dpp v30, v2 row_ror:1 row_mask:0xf bank_mask:0xf
	v_mov_b32_dpp v34, v2 row_ror:2 row_mask:0xf bank_mask:0xf
	v_mov_b32_dpp v31, v3 row_ror:1 row_mask:0xf bank_mask:0xf
	v_mov_b32_dpp v35, v3 row_ror:2 row_mask:0xf bank_mask:0xf
	s_and_saveexec_b64 s[0:1], s[26:27]
	s_cbranch_execz .LBB0_724
	v_cndmask_b32_e64 v22, v22, v14, s[8:9]
	v_cndmask_b32_e64 v23, v23, v15, s[8:9]
	s_waitcnt vmcnt(5)
	v_pk_mul_f32 v[22:23], v[78:79], v[22:23]
	v_cndmask_b32_e64 v18, v10, v18, s[6:7]
	v_cndmask_b32_e64 v19, v11, v19, s[6:7]
	s_waitcnt vmcnt(3)
	v_pk_fma_f32 v[18:19], v[74:75], v[18:19], v[22:23]
	v_cndmask_b32_e64 v42, v62, v34, s[8:9]
	s_waitcnt vmcnt(1)
	v_pk_fma_f32 v[6:7], v[6:7], v[82:83], v[18:19]
	v_cndmask_b32_e64 v43, v63, v35, s[8:9]
	v_cndmask_b32_e64 v20, v20, v12, s[8:9]
	v_cndmask_b32_e64 v21, v21, v13, s[8:9]
	v_cndmask_b32_e64 v46, v30, v59, s[6:7]
	v_cndmask_b32_e64 v47, v31, v61, s[6:7]
	v_pk_mul_f32 v[42:43], v[86:87], v[42:43]
	v_pk_mul_f32 v[20:21], v[76:77], v[20:21]
	v_cndmask_b32_e64 v16, v8, v16, s[6:7]
	v_cndmask_b32_e64 v17, v9, v17, s[6:7]
	v_pk_fma_f32 v[42:43], v[90:91], v[46:47], v[42:43]
	v_pk_fma_f32 v[16:17], v[72:73], v[16:17], v[20:21]
	s_waitcnt vmcnt(0)
	v_pk_fma_f32 v[2:3], v[2:3], v[94:95], v[42:43]
	v_pk_fma_f32 v[4:5], v[4:5], v[80:81], v[16:17]
	v_cndmask_b32_e64 v40, v58, v32, s[8:9]
	v_cndmask_b32_e64 v41, v60, v33, s[8:9]
	v_cndmask_b32_e64 v44, v28, v56, s[6:7]
	v_cndmask_b32_e64 v45, v29, v57, s[6:7]
	v_pk_mul_f32 v[40:41], v[84:85], v[40:41]
	v_pk_fma_f32 v[40:41], v[88:89], v[44:45], v[40:41]
	v_pk_fma_f32 v[0:1], v[0:1], v[92:93], v[40:41]
	v_pk_mul_f32 v[16:17], v[4:5], s[98:99]
	v_pk_mul_f32 v[18:19], v[6:7], s[98:99]
	v_exp_f32_e32 v16, v16
	v_exp_f32_e32 v17, v17
	v_exp_f32_e32 v18, v18
	v_exp_f32_e32 v19, v19
	v_pk_add_f32 v[16:17], v[16:17], s[100:101]
	v_pk_add_f32 v[18:19], v[18:19], s[100:101]
	v_rcp_f32_e32 v16, v16
	v_rcp_f32_e32 v17, v17
	v_rcp_f32_e32 v18, v18
	v_rcp_f32_e32 v19, v19
	v_pk_mul_f32 v[4:5], v[4:5], v[16:17]
	v_pk_mul_f32 v[6:7], v[6:7], v[18:19]
	v_pk_mul_f32 v[0:1], v[4:5], v[0:1]
	v_pk_mul_f32 v[2:3], v[6:7], v[2:3]
	v_cvt_pk_bf16_f32 v0, v0, v1
	v_cvt_pk_bf16_f32 v1, v2, v3
	v_mov_b64_e32 v[2:3], s[30:31]
	v_mad_i64_i32 v[2:3], s[16:17], v136, s67, v[2:3]
	v_lshl_add_u64 v[2:3], v[192:193], 1, v[2:3]
	global_store_dwordx2 v[2:3], v[0:1], off offset:8
.LBB0_724:
	s_or_b64 exec, exec, s[0:1]
	s_nop 1
	v_mov_b32_dpp v0, v24 row_ror:1 row_mask:0xf bank_mask:0xf
	v_mov_b32_dpp v4, v24 row_ror:2 row_mask:0xf bank_mask:0xf
	v_mov_b32_dpp v1, v25 row_ror:1 row_mask:0xf bank_mask:0xf
	v_mov_b32_dpp v5, v25 row_ror:2 row_mask:0xf bank_mask:0xf
	v_mov_b32_dpp v2, v26 row_ror:1 row_mask:0xf bank_mask:0xf
	v_mov_b32_dpp v6, v26 row_ror:2 row_mask:0xf bank_mask:0xf
	v_mov_b32_dpp v3, v27 row_ror:1 row_mask:0xf bank_mask:0xf
	v_mov_b32_dpp v7, v27 row_ror:2 row_mask:0xf bank_mask:0xf
	v_mov_b32_dpp v16, v36 row_ror:1 row_mask:0xf bank_mask:0xf
	v_mov_b32_dpp v20, v36 row_ror:2 row_mask:0xf bank_mask:0xf
	v_mov_b32_dpp v17, v37 row_ror:1 row_mask:0xf bank_mask:0xf
	v_mov_b32_dpp v21, v37 row_ror:2 row_mask:0xf bank_mask:0xf
	v_mov_b32_dpp v18, v38 row_ror:1 row_mask:0xf bank_mask:0xf
	v_mov_b32_dpp v22, v38 row_ror:2 row_mask:0xf bank_mask:0xf
	v_mov_b32_dpp v19, v39 row_ror:1 row_mask:0xf bank_mask:0xf
	v_mov_b32_dpp v23, v39 row_ror:2 row_mask:0xf bank_mask:0xf
	s_and_saveexec_b64 s[0:1], s[28:29]
	s_cbranch_execz .LBB0_726
	v_cndmask_b32_e64 v6, v14, v6, s[8:9]
	v_cndmask_b32_e64 v7, v15, v7, s[8:9]
	s_waitcnt vmcnt(5)
	v_pk_mul_f32 v[6:7], v[78:79], v[6:7]
	v_cndmask_b32_e64 v2, v2, v10, s[6:7]
	v_cndmask_b32_e64 v3, v3, v11, s[6:7]
	s_waitcnt vmcnt(3)
	v_pk_fma_f32 v[2:3], v[74:75], v[2:3], v[6:7]
	v_cndmask_b32_e64 v4, v12, v4, s[8:9]
	s_waitcnt vmcnt(1)
	v_pk_fma_f32 v[2:3], v[26:27], v[82:83], v[2:3]
	v_cndmask_b32_e64 v5, v13, v5, s[8:9]
	v_pk_mul_f32 v[4:5], v[76:77], v[4:5]
	v_cndmask_b32_e64 v0, v0, v8, s[6:7]
	v_cndmask_b32_e64 v1, v1, v9, s[6:7]
	v_pk_fma_f32 v[0:1], v[72:73], v[0:1], v[4:5]
	v_pk_fma_f32 v[0:1], v[24:25], v[80:81], v[0:1]
	v_cndmask_b32_e64 v20, v32, v20, s[8:9]
	v_cndmask_b32_e64 v21, v33, v21, s[8:9]
	v_cndmask_b32_e64 v22, v34, v22, s[8:9]
	v_cndmask_b32_e64 v23, v35, v23, s[8:9]
	v_pk_mul_f32 v[20:21], v[84:85], v[20:21]
	v_pk_mul_f32 v[22:23], v[86:87], v[22:23]
	v_cndmask_b32_e64 v16, v16, v28, s[6:7]
	v_cndmask_b32_e64 v17, v17, v29, s[6:7]
	v_cndmask_b32_e64 v18, v18, v30, s[6:7]
	v_cndmask_b32_e64 v19, v19, v31, s[6:7]
	v_pk_fma_f32 v[18:19], v[90:91], v[18:19], v[22:23]
	v_pk_fma_f32 v[16:17], v[88:89], v[16:17], v[20:21]
	s_waitcnt vmcnt(0)
	v_pk_fma_f32 v[18:19], v[38:39], v[94:95], v[18:19]
	v_pk_fma_f32 v[16:17], v[36:37], v[92:93], v[16:17]
	v_pk_mul_f32 v[4:5], v[0:1], s[98:99]
	v_pk_mul_f32 v[6:7], v[2:3], s[98:99]
	v_exp_f32_e32 v4, v4
	v_exp_f32_e32 v5, v5
	v_exp_f32_e32 v6, v6
	v_exp_f32_e32 v7, v7
	v_pk_add_f32 v[4:5], v[4:5], s[100:101]
	v_pk_add_f32 v[6:7], v[6:7], s[100:101]
	v_rcp_f32_e32 v4, v4
	v_rcp_f32_e32 v5, v5
	v_rcp_f32_e32 v6, v6
	v_rcp_f32_e32 v7, v7
	v_pk_mul_f32 v[0:1], v[0:1], v[4:5]
	v_pk_mul_f32 v[2:3], v[2:3], v[6:7]
	v_pk_mul_f32 v[0:1], v[0:1], v[16:17]
	v_pk_mul_f32 v[2:3], v[2:3], v[18:19]
	v_cvt_pk_bf16_f32 v0, v0, v1
	v_cvt_pk_bf16_f32 v1, v2, v3
	v_mov_b64_e32 v[2:3], s[30:31]
	v_mad_i64_i32 v[2:3], s[16:17], v137, s67, v[2:3]
	v_lshl_add_u64 v[2:3], v[192:193], 1, v[2:3]
	global_store_dwordx2 v[2:3], v[0:1], off offset:8
